# MFMA order: B-fragment(src0)-stationary Gray code with back-to-back accumulate pairs per 32-MFMA segment
# baseline (speedup 1.0000x reference)
.LBB0_139:
	s_add_u32 s22, s18, 0xfff00080
	s_addc_u32 s23, s19, -1
	s_add_i32 s49, 0, 0x10000
	s_cmp_eq_u32 s48, 60
	s_cselect_b32 s25, s9, s23
	s_cselect_b32 s24, s44, s22
	s_cselect_b32 s23, s7, s47
	s_cselect_b32 s22, s45, s46
	s_add_i32 s52, 0, 0x14000
	v_add_u32_e32 v156, s49, v145
	v_add_u32_e32 v172, s52, v145
	ds_read_b128 v[140:143], v156
	ds_read_b128 v[148:151], v156 offset:1024
	ds_read_b128 v[152:155], v156 offset:2048
	ds_read_b128 v[156:159], v156 offset:3072
	ds_read_b128 v[160:163], v172
	ds_read_b128 v[164:167], v172 offset:1024
	ds_read_b128 v[168:171], v172 offset:2048
	ds_read_b128 v[190:193], v172 offset:3072
	v_lshl_add_u64 v[172:173], s[18:19], 0, v[136:137]
	s_add_i32 m0, s31, 0xc000
	ds_read_b128 v[194:197], v147
	ds_read_b128 v[198:201], v147 offset:1024
	ds_read_b128 v[202:205], v147 offset:2048
	ds_read_b128 v[206:209], v147 offset:3072
	ds_read_b128 v[228:231], v147 offset:4096
	ds_read_b128 v[232:235], v147 offset:5120
	ds_read_b128 v[236:239], v147 offset:6144
	ds_read_b128 v[240:243], v147 offset:7168
	global_load_lds_dwordx4 v[172:173], off
	v_lshl_add_u64 v[172:173], s[18:19], 0, v[138:139]
	s_add_i32 m0, s31, 0xe000
	s_nop 0
	global_load_lds_dwordx4 v[172:173], off
	s_waitcnt vmcnt(8)
	s_waitcnt lgkmcnt(0)
	s_barrier
	s_setprio 1
	s_waitcnt lgkmcnt(0)
	v_mfma_f32_16x16x32_bf16 v[126:129], v[140:143], v[194:197], v[126:129]
	v_mfma_f32_16x16x32_bf16 v[126:129], v[148:151], v[198:201], v[126:129]
	v_mfma_f32_16x16x32_bf16 v[118:121], v[148:151], v[206:209], v[118:121]
	v_mfma_f32_16x16x32_bf16 v[118:121], v[140:143], v[202:205], v[118:121]
	v_mfma_f32_16x16x32_bf16 v[102:105], v[140:143], v[228:231], v[102:105]
	v_mfma_f32_16x16x32_bf16 v[102:105], v[148:151], v[232:235], v[102:105]
	v_mfma_f32_16x16x32_bf16 v[86:89], v[148:151], v[240:243], v[86:89]
	v_mfma_f32_16x16x32_bf16 v[86:89], v[140:143], v[236:239], v[86:89]
	v_mfma_f32_16x16x32_bf16 v[78:81], v[152:155], v[236:239], v[78:81]
	v_mfma_f32_16x16x32_bf16 v[78:81], v[156:159], v[240:243], v[78:81]
	v_mfma_f32_16x16x32_bf16 v[94:97], v[156:159], v[232:235], v[94:97]
	v_mfma_f32_16x16x32_bf16 v[94:97], v[152:155], v[228:231], v[94:97]
	v_mfma_f32_16x16x32_bf16 v[110:113], v[152:155], v[202:205], v[110:113]
	v_mfma_f32_16x16x32_bf16 v[110:113], v[156:159], v[206:209], v[110:113]
	v_mfma_f32_16x16x32_bf16 v[122:125], v[156:159], v[198:201], v[122:125]
	v_mfma_f32_16x16x32_bf16 v[122:125], v[152:155], v[194:197], v[122:125]
	s_setprio 0
	s_setprio 1
	v_mfma_f32_16x16x32_bf16 v[114:117], v[160:163], v[194:197], v[114:117]
	v_mfma_f32_16x16x32_bf16 v[114:117], v[164:167], v[198:201], v[114:117]
	v_mfma_f32_16x16x32_bf16 v[98:101], v[164:167], v[206:209], v[98:101]
	v_mfma_f32_16x16x32_bf16 v[98:101], v[160:163], v[202:205], v[98:101]
	v_mfma_f32_16x16x32_bf16 v[82:85], v[160:163], v[228:231], v[82:85]
	v_mfma_f32_16x16x32_bf16 v[82:85], v[164:167], v[232:235], v[82:85]
	v_mfma_f32_16x16x32_bf16 v[70:73], v[164:167], v[240:243], v[70:73]
	v_mfma_f32_16x16x32_bf16 v[70:73], v[160:163], v[236:239], v[70:73]
	v_mfma_f32_16x16x32_bf16 v[66:69], v[168:171], v[236:239], v[66:69]
	v_mfma_f32_16x16x32_bf16 v[66:69], v[190:193], v[240:243], v[66:69]
	v_mfma_f32_16x16x32_bf16 v[74:77], v[190:193], v[232:235], v[74:77]
	v_mfma_f32_16x16x32_bf16 v[74:77], v[168:171], v[228:231], v[74:77]
	v_mfma_f32_16x16x32_bf16 v[90:93], v[168:171], v[202:205], v[90:93]
	v_mfma_f32_16x16x32_bf16 v[90:93], v[190:193], v[206:209], v[90:93]
	v_mfma_f32_16x16x32_bf16 v[106:109], v[190:193], v[198:201], v[106:109]
	v_mfma_f32_16x16x32_bf16 v[106:109], v[168:171], v[194:197], v[106:109]
	s_setprio 0
	s_barrier
	s_add_i32 s49, s49, s26
	v_lshl_add_u64 v[172:173], s[22:23], 0, v[0:1]
	s_mov_b32 m0, s49
	ds_read_b128 v[194:197], v147 offset:16384
	ds_read_b128 v[198:201], v147 offset:17408
	ds_read_b128 v[202:205], v147 offset:18432
	ds_read_b128 v[206:209], v147 offset:19456
	ds_read_b128 v[228:231], v147 offset:20480
	ds_read_b128 v[232:235], v147 offset:21504
	ds_read_b128 v[236:239], v147 offset:22528
	ds_read_b128 v[240:243], v147 offset:23552
	global_load_lds_dwordx4 v[172:173], off
	s_add_i32 m0, s49, 0x2000
	s_add_u32 s50, s22, 0x100000
	v_lshl_add_u64 v[178:179], s[22:23], 0, v[130:131]
	s_addc_u32 s51, s23, 0
	s_add_i32 s49, s52, s26
	global_load_lds_dwordx4 v[178:179], off
	v_lshl_add_u64 v[180:181], s[50:51], 0, v[0:1]
	s_mov_b32 m0, s49
	v_lshl_add_u64 v[210:211], s[24:25], 0, v[132:133]
	global_load_lds_dwordx4 v[180:181], off
	v_lshl_add_u64 v[180:181], s[50:51], 0, v[130:131]
	s_add_i32 m0, s49, 0x2000
	s_nop 0
	global_load_lds_dwordx4 v[180:181], off
	v_lshl_add_u64 v[180:181], s[24:25], 0, v[134:135]
	s_mov_b32 m0, s31
	s_nop 0
	global_load_lds_dwordx4 v[180:181], off
	s_mov_b32 m0, s36
	s_nop 0
	global_load_lds_dwordx4 v[210:211], off
	s_waitcnt vmcnt(8)
	s_waitcnt lgkmcnt(0)
	s_barrier
	s_setprio 1
	s_waitcnt lgkmcnt(0)
	v_mfma_f32_16x16x32_bf16 v[62:65], v[140:143], v[194:197], v[62:65]
	v_mfma_f32_16x16x32_bf16 v[62:65], v[148:151], v[198:201], v[62:65]
	v_mfma_f32_16x16x32_bf16 v[54:57], v[148:151], v[206:209], v[54:57]
	v_mfma_f32_16x16x32_bf16 v[54:57], v[140:143], v[202:205], v[54:57]
	v_mfma_f32_16x16x32_bf16 v[38:41], v[140:143], v[228:231], v[38:41]
	v_mfma_f32_16x16x32_bf16 v[38:41], v[148:151], v[232:235], v[38:41]
	v_mfma_f32_16x16x32_bf16 v[22:25], v[148:151], v[240:243], v[22:25]
	v_mfma_f32_16x16x32_bf16 v[22:25], v[140:143], v[236:239], v[22:25]
	v_mfma_f32_16x16x32_bf16 v[14:17], v[152:155], v[236:239], v[14:17]
	v_mfma_f32_16x16x32_bf16 v[14:17], v[156:159], v[240:243], v[14:17]
	v_mfma_f32_16x16x32_bf16 v[30:33], v[156:159], v[232:235], v[30:33]
	v_mfma_f32_16x16x32_bf16 v[30:33], v[152:155], v[228:231], v[30:33]
	v_mfma_f32_16x16x32_bf16 v[46:49], v[152:155], v[202:205], v[46:49]
	v_mfma_f32_16x16x32_bf16 v[46:49], v[156:159], v[206:209], v[46:49]
	v_mfma_f32_16x16x32_bf16 v[58:61], v[156:159], v[198:201], v[58:61]
	v_mfma_f32_16x16x32_bf16 v[58:61], v[152:155], v[194:197], v[58:61]
	s_setprio 0
	s_setprio 1
	v_mfma_f32_16x16x32_bf16 v[50:53], v[160:163], v[194:197], v[50:53]
	v_mfma_f32_16x16x32_bf16 v[50:53], v[164:167], v[198:201], v[50:53]
	v_mfma_f32_16x16x32_bf16 v[34:37], v[164:167], v[206:209], v[34:37]
	v_mfma_f32_16x16x32_bf16 v[34:37], v[160:163], v[202:205], v[34:37]
	v_mfma_f32_16x16x32_bf16 v[18:21], v[160:163], v[228:231], v[18:21]
	v_mfma_f32_16x16x32_bf16 v[18:21], v[164:167], v[232:235], v[18:21]
	v_mfma_f32_16x16x32_bf16 v[6:9], v[164:167], v[240:243], v[6:9]
	v_mfma_f32_16x16x32_bf16 v[6:9], v[160:163], v[236:239], v[6:9]
	v_mfma_f32_16x16x32_bf16 v[2:5], v[168:171], v[236:239], v[2:5]
	v_mfma_f32_16x16x32_bf16 v[2:5], v[190:193], v[240:243], v[2:5]
	v_mfma_f32_16x16x32_bf16 v[10:13], v[190:193], v[232:235], v[10:13]
	v_mfma_f32_16x16x32_bf16 v[10:13], v[168:171], v[228:231], v[10:13]
	v_mfma_f32_16x16x32_bf16 v[26:29], v[168:171], v[202:205], v[26:29]
	v_mfma_f32_16x16x32_bf16 v[26:29], v[190:193], v[206:209], v[26:29]
	v_mfma_f32_16x16x32_bf16 v[42:45], v[190:193], v[198:201], v[42:45]
	v_mfma_f32_16x16x32_bf16 v[42:45], v[168:171], v[194:197], v[42:45]
	s_setprio 0
	s_barrier
	s_add_i32 s49, 0, 0x18000
	s_add_i32 s50, 0, 0x1c000
	v_add_u32_e32 v156, s49, v145
	v_add_u32_e32 v175, s50, v145
	ds_read_b128 v[140:143], v156
	ds_read_b128 v[148:151], v156 offset:1024
	ds_read_b128 v[152:155], v156 offset:2048
	ds_read_b128 v[156:159], v156 offset:3072
	ds_read_b128 v[160:163], v175
	ds_read_b128 v[164:167], v175 offset:1024
	ds_read_b128 v[168:171], v175 offset:2048
	ds_read_b128 v[190:193], v175 offset:3072
	s_add_u32 s24, s24, 0x100000
	s_addc_u32 s25, s25, 0
	s_mov_b32 m0, s37
	v_lshl_add_u64 v[244:245], s[24:25], 0, v[134:135]
	ds_read_b128 v[194:197], v147 offset:32768
	ds_read_b128 v[198:201], v147 offset:33792
	ds_read_b128 v[202:205], v147 offset:34816
	ds_read_b128 v[206:209], v147 offset:35840
	ds_read_b128 v[228:231], v147 offset:36864
	ds_read_b128 v[232:235], v147 offset:37888
	ds_read_b128 v[236:239], v147 offset:38912
	ds_read_b128 v[240:243], v147 offset:39936
	global_load_lds_dwordx4 v[244:245], off
	v_lshl_add_u64 v[244:245], s[24:25], 0, v[132:133]
	s_mov_b32 m0, s38
	s_nop 0
	global_load_lds_dwordx4 v[244:245], off
	s_waitcnt vmcnt(8)
	s_waitcnt lgkmcnt(0)
	s_barrier
	s_setprio 1
	s_waitcnt lgkmcnt(0)
	v_mfma_f32_16x16x32_bf16 v[126:129], v[140:143], v[194:197], v[126:129]
	v_mfma_f32_16x16x32_bf16 v[126:129], v[148:151], v[198:201], v[126:129]
	v_mfma_f32_16x16x32_bf16 v[118:121], v[148:151], v[206:209], v[118:121]
	v_mfma_f32_16x16x32_bf16 v[118:121], v[140:143], v[202:205], v[118:121]
	v_mfma_f32_16x16x32_bf16 v[102:105], v[140:143], v[228:231], v[102:105]
	v_mfma_f32_16x16x32_bf16 v[102:105], v[148:151], v[232:235], v[102:105]
	v_mfma_f32_16x16x32_bf16 v[86:89], v[148:151], v[240:243], v[86:89]
	v_mfma_f32_16x16x32_bf16 v[86:89], v[140:143], v[236:239], v[86:89]
	v_mfma_f32_16x16x32_bf16 v[78:81], v[152:155], v[236:239], v[78:81]
	v_mfma_f32_16x16x32_bf16 v[78:81], v[156:159], v[240:243], v[78:81]
	v_mfma_f32_16x16x32_bf16 v[94:97], v[156:159], v[232:235], v[94:97]
	v_mfma_f32_16x16x32_bf16 v[94:97], v[152:155], v[228:231], v[94:97]
	v_mfma_f32_16x16x32_bf16 v[110:113], v[152:155], v[202:205], v[110:113]
	v_mfma_f32_16x16x32_bf16 v[110:113], v[156:159], v[206:209], v[110:113]
	v_mfma_f32_16x16x32_bf16 v[122:125], v[156:159], v[198:201], v[122:125]
	v_mfma_f32_16x16x32_bf16 v[122:125], v[152:155], v[194:197], v[122:125]
	s_setprio 0
	s_setprio 1
	v_mfma_f32_16x16x32_bf16 v[114:117], v[160:163], v[194:197], v[114:117]
	v_mfma_f32_16x16x32_bf16 v[114:117], v[164:167], v[198:201], v[114:117]
	v_mfma_f32_16x16x32_bf16 v[98:101], v[164:167], v[206:209], v[98:101]
	v_mfma_f32_16x16x32_bf16 v[98:101], v[160:163], v[202:205], v[98:101]
	v_mfma_f32_16x16x32_bf16 v[82:85], v[160:163], v[228:231], v[82:85]
	v_mfma_f32_16x16x32_bf16 v[82:85], v[164:167], v[232:235], v[82:85]
	v_mfma_f32_16x16x32_bf16 v[70:73], v[164:167], v[240:243], v[70:73]
	v_mfma_f32_16x16x32_bf16 v[70:73], v[160:163], v[236:239], v[70:73]
	v_mfma_f32_16x16x32_bf16 v[66:69], v[168:171], v[236:239], v[66:69]
	v_mfma_f32_16x16x32_bf16 v[66:69], v[190:193], v[240:243], v[66:69]
	v_mfma_f32_16x16x32_bf16 v[74:77], v[190:193], v[232:235], v[74:77]
	v_mfma_f32_16x16x32_bf16 v[74:77], v[168:171], v[228:231], v[74:77]
	v_mfma_f32_16x16x32_bf16 v[90:93], v[168:171], v[202:205], v[90:93]
	v_mfma_f32_16x16x32_bf16 v[90:93], v[190:193], v[206:209], v[90:93]
	v_mfma_f32_16x16x32_bf16 v[106:109], v[190:193], v[198:201], v[106:109]
	v_mfma_f32_16x16x32_bf16 v[106:109], v[168:171], v[194:197], v[106:109]
	s_setprio 0
	s_barrier
	s_add_i32 s24, s49, s26
	v_lshl_add_u64 v[172:173], v[172:173], 0, s[34:35]
	s_mov_b32 m0, s24
	ds_read_b128 v[194:197], v147 offset:49152
	ds_read_b128 v[198:201], v147 offset:50176
	ds_read_b128 v[202:205], v147 offset:51200
	ds_read_b128 v[206:209], v147 offset:52224
	ds_read_b128 v[228:231], v147 offset:53248
	ds_read_b128 v[232:235], v147 offset:54272
	ds_read_b128 v[236:239], v147 offset:55296
	ds_read_b128 v[240:243], v147 offset:56320
	global_load_lds_dwordx4 v[172:173], off
	s_add_i32 m0, s24, 0x2000
	s_add_u32 s22, s22, 0x100080
	v_lshl_add_u64 v[172:173], v[178:179], 0, s[34:35]
	s_addc_u32 s23, s23, 0
	s_add_i32 s24, s50, s26
	global_load_lds_dwordx4 v[172:173], off
	v_lshl_add_u64 v[172:173], s[22:23], 0, v[0:1]
	s_mov_b32 m0, s24
	s_nop 0
	global_load_lds_dwordx4 v[172:173], off
	v_lshl_add_u64 v[172:173], s[22:23], 0, v[130:131]
	s_add_i32 m0, s24, 0x2000
	s_nop 0
	global_load_lds_dwordx4 v[172:173], off
	v_lshl_add_u64 v[172:173], v[180:181], 0, s[34:35]
	s_mov_b32 m0, s39
	s_nop 0
	global_load_lds_dwordx4 v[172:173], off
	v_lshl_add_u64 v[172:173], v[210:211], 0, s[34:35]
	s_mov_b32 m0, s40
	s_nop 0
	global_load_lds_dwordx4 v[172:173], off
	s_waitcnt vmcnt(8)
	s_waitcnt lgkmcnt(0)
	s_barrier
	s_setprio 1
	s_waitcnt lgkmcnt(0)
	v_mfma_f32_16x16x32_bf16 v[62:65], v[140:143], v[194:197], v[62:65]
	v_mfma_f32_16x16x32_bf16 v[62:65], v[148:151], v[198:201], v[62:65]
	v_mfma_f32_16x16x32_bf16 v[54:57], v[148:151], v[206:209], v[54:57]
	v_mfma_f32_16x16x32_bf16 v[54:57], v[140:143], v[202:205], v[54:57]
	v_mfma_f32_16x16x32_bf16 v[38:41], v[140:143], v[228:231], v[38:41]
	v_mfma_f32_16x16x32_bf16 v[38:41], v[148:151], v[232:235], v[38:41]
	v_mfma_f32_16x16x32_bf16 v[22:25], v[148:151], v[240:243], v[22:25]
	v_mfma_f32_16x16x32_bf16 v[22:25], v[140:143], v[236:239], v[22:25]
	v_mfma_f32_16x16x32_bf16 v[14:17], v[152:155], v[236:239], v[14:17]
	v_mfma_f32_16x16x32_bf16 v[14:17], v[156:159], v[240:243], v[14:17]
	v_mfma_f32_16x16x32_bf16 v[30:33], v[156:159], v[232:235], v[30:33]
	v_mfma_f32_16x16x32_bf16 v[30:33], v[152:155], v[228:231], v[30:33]
	v_mfma_f32_16x16x32_bf16 v[46:49], v[152:155], v[202:205], v[46:49]
	v_mfma_f32_16x16x32_bf16 v[46:49], v[156:159], v[206:209], v[46:49]
	v_mfma_f32_16x16x32_bf16 v[58:61], v[156:159], v[198:201], v[58:61]
	v_mfma_f32_16x16x32_bf16 v[58:61], v[152:155], v[194:197], v[58:61]
	s_setprio 0
	s_setprio 1
	v_mfma_f32_16x16x32_bf16 v[50:53], v[160:163], v[194:197], v[50:53]
	v_mfma_f32_16x16x32_bf16 v[50:53], v[164:167], v[198:201], v[50:53]
	v_mfma_f32_16x16x32_bf16 v[34:37], v[164:167], v[206:209], v[34:37]
	v_mfma_f32_16x16x32_bf16 v[34:37], v[160:163], v[202:205], v[34:37]
	v_mfma_f32_16x16x32_bf16 v[18:21], v[160:163], v[228:231], v[18:21]
	v_mfma_f32_16x16x32_bf16 v[18:21], v[164:167], v[232:235], v[18:21]
	v_mfma_f32_16x16x32_bf16 v[6:9], v[164:167], v[240:243], v[6:9]
	v_mfma_f32_16x16x32_bf16 v[6:9], v[160:163], v[236:239], v[6:9]
	v_mfma_f32_16x16x32_bf16 v[2:5], v[168:171], v[236:239], v[2:5]
	v_mfma_f32_16x16x32_bf16 v[2:5], v[190:193], v[240:243], v[2:5]
	v_mfma_f32_16x16x32_bf16 v[10:13], v[190:193], v[232:235], v[10:13]
	v_mfma_f32_16x16x32_bf16 v[10:13], v[168:171], v[228:231], v[10:13]
	v_mfma_f32_16x16x32_bf16 v[26:29], v[168:171], v[202:205], v[26:29]
	v_mfma_f32_16x16x32_bf16 v[26:29], v[190:193], v[206:209], v[26:29]
	v_mfma_f32_16x16x32_bf16 v[42:45], v[190:193], v[198:201], v[42:45]
	v_mfma_f32_16x16x32_bf16 v[42:45], v[168:171], v[194:197], v[42:45]
	s_setprio 0
	s_barrier
	s_add_i32 s48, s48, 2
	s_add_u32 s18, s18, 0x100
	s_addc_u32 s19, s19, 0
	s_add_u32 s46, s46, 0x100
	s_addc_u32 s47, s47, 0
	s_cmp_gt_u32 s48, 61
	s_cbranch_scc0 .LBB0_139
	s_and_b64 vcc, exec, s[4:5]
	s_cbranch_vccz .LBB0_142
	s_barrier

.LBB0_575:
	s_add_u32 s22, s18, 0xfff00080
	s_addc_u32 s23, s19, -1
	s_add_i32 s53, 0, 0x10000
	s_cmp_eq_u32 s52, 60
	s_cselect_b32 s25, s9, s23
	s_cselect_b32 s24, s48, s22
	v_add_u32_e32 v140, s53, v143
	s_cselect_b32 s23, s7, s51
	s_cselect_b32 s22, s49, s50
	s_add_i32 s56, 0, 0x14000
	ds_read_b128 v[146:149], v140
	ds_read_b128 v[150:153], v140 offset:1024
	ds_read_b128 v[154:157], v140 offset:2048
	ds_read_b128 v[158:161], v140 offset:3072
	v_add_u32_e32 v140, s56, v143
	ds_read_b128 v[162:165], v140
	ds_read_b128 v[166:169], v140 offset:1024
	ds_read_b128 v[170:173], v140 offset:2048
	ds_read_b128 v[178:181], v140 offset:3072
	v_lshl_add_u64 v[140:141], s[18:19], 0, v[136:137]
	s_add_i32 m0, s39, 0xc000
	ds_read_b128 v[190:193], v145
	ds_read_b128 v[194:197], v145 offset:1024
	ds_read_b128 v[198:201], v145 offset:2048
	ds_read_b128 v[202:205], v145 offset:3072
	ds_read_b128 v[206:209], v145 offset:4096
	ds_read_b128 v[228:231], v145 offset:5120
	ds_read_b128 v[232:235], v145 offset:6144
	ds_read_b128 v[236:239], v145 offset:7168
	global_load_lds_dwordx4 v[140:141], off
	v_lshl_add_u64 v[140:141], s[18:19], 0, v[138:139]
	s_add_i32 m0, s39, 0xe000
	s_nop 0
	global_load_lds_dwordx4 v[140:141], off
	s_waitcnt vmcnt(8)
	s_waitcnt lgkmcnt(0)
	s_barrier
	s_setprio 1
	s_waitcnt lgkmcnt(0)
	v_mfma_f32_16x16x32_bf16 v[126:129], v[146:149], v[190:193], v[126:129]
	v_mfma_f32_16x16x32_bf16 v[126:129], v[150:153], v[194:197], v[126:129]
	v_mfma_f32_16x16x32_bf16 v[118:121], v[150:153], v[202:205], v[118:121]
	v_mfma_f32_16x16x32_bf16 v[118:121], v[146:149], v[198:201], v[118:121]
	v_mfma_f32_16x16x32_bf16 v[102:105], v[146:149], v[206:209], v[102:105]
	v_mfma_f32_16x16x32_bf16 v[102:105], v[150:153], v[228:231], v[102:105]
	v_mfma_f32_16x16x32_bf16 v[86:89], v[150:153], v[236:239], v[86:89]
	v_mfma_f32_16x16x32_bf16 v[86:89], v[146:149], v[232:235], v[86:89]
	v_mfma_f32_16x16x32_bf16 v[78:81], v[154:157], v[232:235], v[78:81]
	v_mfma_f32_16x16x32_bf16 v[78:81], v[158:161], v[236:239], v[78:81]
	v_mfma_f32_16x16x32_bf16 v[94:97], v[158:161], v[228:231], v[94:97]
	v_mfma_f32_16x16x32_bf16 v[94:97], v[154:157], v[206:209], v[94:97]
	v_mfma_f32_16x16x32_bf16 v[110:113], v[154:157], v[198:201], v[110:113]
	v_mfma_f32_16x16x32_bf16 v[110:113], v[158:161], v[202:205], v[110:113]
	v_mfma_f32_16x16x32_bf16 v[122:125], v[158:161], v[194:197], v[122:125]
	v_mfma_f32_16x16x32_bf16 v[122:125], v[154:157], v[190:193], v[122:125]
	s_setprio 0
	s_setprio 1
	v_mfma_f32_16x16x32_bf16 v[114:117], v[162:165], v[190:193], v[114:117]
	v_mfma_f32_16x16x32_bf16 v[114:117], v[166:169], v[194:197], v[114:117]
	v_mfma_f32_16x16x32_bf16 v[98:101], v[166:169], v[202:205], v[98:101]
	v_mfma_f32_16x16x32_bf16 v[98:101], v[162:165], v[198:201], v[98:101]
	v_mfma_f32_16x16x32_bf16 v[82:85], v[162:165], v[206:209], v[82:85]
	v_mfma_f32_16x16x32_bf16 v[82:85], v[166:169], v[228:231], v[82:85]
	v_mfma_f32_16x16x32_bf16 v[70:73], v[166:169], v[236:239], v[70:73]
	v_mfma_f32_16x16x32_bf16 v[70:73], v[162:165], v[232:235], v[70:73]
	v_mfma_f32_16x16x32_bf16 v[66:69], v[170:173], v[232:235], v[66:69]
	v_mfma_f32_16x16x32_bf16 v[66:69], v[178:181], v[236:239], v[66:69]
	v_mfma_f32_16x16x32_bf16 v[74:77], v[178:181], v[228:231], v[74:77]
	v_mfma_f32_16x16x32_bf16 v[74:77], v[170:173], v[206:209], v[74:77]
	v_mfma_f32_16x16x32_bf16 v[90:93], v[170:173], v[198:201], v[90:93]
	v_mfma_f32_16x16x32_bf16 v[90:93], v[178:181], v[202:205], v[90:93]
	v_mfma_f32_16x16x32_bf16 v[106:109], v[178:181], v[194:197], v[106:109]
	v_mfma_f32_16x16x32_bf16 v[106:109], v[170:173], v[190:193], v[106:109]
	s_setprio 0
	s_barrier
	s_add_i32 s53, s53, s38
	v_lshl_add_u64 v[140:141], s[22:23], 0, v[0:1]
	s_mov_b32 m0, s53
	ds_read_b128 v[190:193], v145 offset:16384
	ds_read_b128 v[194:197], v145 offset:17408
	ds_read_b128 v[198:201], v145 offset:18432
	ds_read_b128 v[202:205], v145 offset:19456
	ds_read_b128 v[206:209], v145 offset:20480
	ds_read_b128 v[228:231], v145 offset:21504
	ds_read_b128 v[232:235], v145 offset:22528
	ds_read_b128 v[236:239], v145 offset:23552
	global_load_lds_dwordx4 v[140:141], off
	s_add_i32 m0, s53, 0x2000
	s_add_u32 s54, s22, 0x100000
	v_lshl_add_u64 v[186:187], s[22:23], 0, v[130:131]
	s_addc_u32 s55, s23, 0
	s_add_i32 s53, s56, s38
	global_load_lds_dwordx4 v[186:187], off
	v_lshl_add_u64 v[188:189], s[54:55], 0, v[0:1]
	s_mov_b32 m0, s53
	v_lshl_add_u64 v[210:211], s[24:25], 0, v[132:133]
	global_load_lds_dwordx4 v[188:189], off
	v_lshl_add_u64 v[188:189], s[54:55], 0, v[130:131]
	s_add_i32 m0, s53, 0x2000
	s_nop 0
	global_load_lds_dwordx4 v[188:189], off
	v_lshl_add_u64 v[188:189], s[24:25], 0, v[134:135]
	s_mov_b32 m0, s39
	s_nop 0
	global_load_lds_dwordx4 v[188:189], off
	s_mov_b32 m0, s40
	s_nop 0
	global_load_lds_dwordx4 v[210:211], off
	s_waitcnt vmcnt(8)
	s_waitcnt lgkmcnt(0)
	s_barrier
	s_setprio 1
	s_waitcnt lgkmcnt(0)
	v_mfma_f32_16x16x32_bf16 v[62:65], v[146:149], v[190:193], v[62:65]
	v_mfma_f32_16x16x32_bf16 v[62:65], v[150:153], v[194:197], v[62:65]
	v_mfma_f32_16x16x32_bf16 v[54:57], v[150:153], v[202:205], v[54:57]
	v_mfma_f32_16x16x32_bf16 v[54:57], v[146:149], v[198:201], v[54:57]
	v_mfma_f32_16x16x32_bf16 v[38:41], v[146:149], v[206:209], v[38:41]
	v_mfma_f32_16x16x32_bf16 v[38:41], v[150:153], v[228:231], v[38:41]
	v_mfma_f32_16x16x32_bf16 v[22:25], v[150:153], v[236:239], v[22:25]
	v_mfma_f32_16x16x32_bf16 v[22:25], v[146:149], v[232:235], v[22:25]
	v_mfma_f32_16x16x32_bf16 v[14:17], v[154:157], v[232:235], v[14:17]
	v_mfma_f32_16x16x32_bf16 v[14:17], v[158:161], v[236:239], v[14:17]
	v_mfma_f32_16x16x32_bf16 v[30:33], v[158:161], v[228:231], v[30:33]
	v_mfma_f32_16x16x32_bf16 v[30:33], v[154:157], v[206:209], v[30:33]
	v_mfma_f32_16x16x32_bf16 v[46:49], v[154:157], v[198:201], v[46:49]
	v_mfma_f32_16x16x32_bf16 v[46:49], v[158:161], v[202:205], v[46:49]
	v_mfma_f32_16x16x32_bf16 v[58:61], v[158:161], v[194:197], v[58:61]
	v_mfma_f32_16x16x32_bf16 v[58:61], v[154:157], v[190:193], v[58:61]
	s_setprio 0
	s_setprio 1
	v_mfma_f32_16x16x32_bf16 v[50:53], v[162:165], v[190:193], v[50:53]
	v_mfma_f32_16x16x32_bf16 v[50:53], v[166:169], v[194:197], v[50:53]
	v_mfma_f32_16x16x32_bf16 v[34:37], v[166:169], v[202:205], v[34:37]
	v_mfma_f32_16x16x32_bf16 v[34:37], v[162:165], v[198:201], v[34:37]
	v_mfma_f32_16x16x32_bf16 v[18:21], v[162:165], v[206:209], v[18:21]
	v_mfma_f32_16x16x32_bf16 v[18:21], v[166:169], v[228:231], v[18:21]
	v_mfma_f32_16x16x32_bf16 v[6:9], v[166:169], v[236:239], v[6:9]
	v_mfma_f32_16x16x32_bf16 v[6:9], v[162:165], v[232:235], v[6:9]
	v_mfma_f32_16x16x32_bf16 v[2:5], v[170:173], v[232:235], v[2:5]
	v_mfma_f32_16x16x32_bf16 v[2:5], v[178:181], v[236:239], v[2:5]
	v_mfma_f32_16x16x32_bf16 v[10:13], v[178:181], v[228:231], v[10:13]
	v_mfma_f32_16x16x32_bf16 v[10:13], v[170:173], v[206:209], v[10:13]
	v_mfma_f32_16x16x32_bf16 v[26:29], v[170:173], v[198:201], v[26:29]
	v_mfma_f32_16x16x32_bf16 v[26:29], v[178:181], v[202:205], v[26:29]
	v_mfma_f32_16x16x32_bf16 v[42:45], v[178:181], v[194:197], v[42:45]
	v_mfma_f32_16x16x32_bf16 v[42:45], v[170:173], v[190:193], v[42:45]
	s_setprio 0
	s_barrier
	s_add_i32 s53, 0, 0x18000
	s_add_i32 s54, 0, 0x1c000
	v_add_u32_e32 v158, s53, v143
	v_add_u32_e32 v175, s54, v143
	ds_read_b128 v[146:149], v158
	ds_read_b128 v[150:153], v158 offset:1024
	ds_read_b128 v[154:157], v158 offset:2048
	ds_read_b128 v[158:161], v158 offset:3072
	ds_read_b128 v[162:165], v175
	ds_read_b128 v[166:169], v175 offset:1024
	ds_read_b128 v[170:173], v175 offset:2048
	ds_read_b128 v[178:181], v175 offset:3072
	s_add_u32 s24, s24, 0x100000
	s_addc_u32 s25, s25, 0
	s_mov_b32 m0, s41
	v_lshl_add_u64 v[226:227], s[24:25], 0, v[134:135]
	ds_read_b128 v[190:193], v145 offset:32768
	ds_read_b128 v[194:197], v145 offset:33792
	ds_read_b128 v[198:201], v145 offset:34816
	ds_read_b128 v[202:205], v145 offset:35840
	ds_read_b128 v[206:209], v145 offset:36864
	ds_read_b128 v[228:231], v145 offset:37888
	ds_read_b128 v[232:235], v145 offset:38912
	ds_read_b128 v[236:239], v145 offset:39936
	global_load_lds_dwordx4 v[226:227], off
	v_lshl_add_u64 v[226:227], s[24:25], 0, v[132:133]
	s_mov_b32 m0, s42
	s_nop 0
	global_load_lds_dwordx4 v[226:227], off
	s_waitcnt vmcnt(8)
	s_waitcnt lgkmcnt(0)
	s_barrier
	s_setprio 1
	s_waitcnt lgkmcnt(0)
	v_mfma_f32_16x16x32_bf16 v[126:129], v[146:149], v[190:193], v[126:129]
	v_mfma_f32_16x16x32_bf16 v[126:129], v[150:153], v[194:197], v[126:129]
	v_mfma_f32_16x16x32_bf16 v[118:121], v[150:153], v[202:205], v[118:121]
	v_mfma_f32_16x16x32_bf16 v[118:121], v[146:149], v[198:201], v[118:121]
	v_mfma_f32_16x16x32_bf16 v[102:105], v[146:149], v[206:209], v[102:105]
	v_mfma_f32_16x16x32_bf16 v[102:105], v[150:153], v[228:231], v[102:105]
	v_mfma_f32_16x16x32_bf16 v[86:89], v[150:153], v[236:239], v[86:89]
	v_mfma_f32_16x16x32_bf16 v[86:89], v[146:149], v[232:235], v[86:89]
	v_mfma_f32_16x16x32_bf16 v[78:81], v[154:157], v[232:235], v[78:81]
	v_mfma_f32_16x16x32_bf16 v[78:81], v[158:161], v[236:239], v[78:81]
	v_mfma_f32_16x16x32_bf16 v[94:97], v[158:161], v[228:231], v[94:97]
	v_mfma_f32_16x16x32_bf16 v[94:97], v[154:157], v[206:209], v[94:97]
	v_mfma_f32_16x16x32_bf16 v[110:113], v[154:157], v[198:201], v[110:113]
	v_mfma_f32_16x16x32_bf16 v[110:113], v[158:161], v[202:205], v[110:113]
	v_mfma_f32_16x16x32_bf16 v[122:125], v[158:161], v[194:197], v[122:125]
	v_mfma_f32_16x16x32_bf16 v[122:125], v[154:157], v[190:193], v[122:125]
	s_setprio 0
	s_setprio 1
	v_mfma_f32_16x16x32_bf16 v[114:117], v[162:165], v[190:193], v[114:117]
	v_mfma_f32_16x16x32_bf16 v[114:117], v[166:169], v[194:197], v[114:117]
	v_mfma_f32_16x16x32_bf16 v[98:101], v[166:169], v[202:205], v[98:101]
	v_mfma_f32_16x16x32_bf16 v[98:101], v[162:165], v[198:201], v[98:101]
	v_mfma_f32_16x16x32_bf16 v[82:85], v[162:165], v[206:209], v[82:85]
	v_mfma_f32_16x16x32_bf16 v[82:85], v[166:169], v[228:231], v[82:85]
	v_mfma_f32_16x16x32_bf16 v[70:73], v[166:169], v[236:239], v[70:73]
	v_mfma_f32_16x16x32_bf16 v[70:73], v[162:165], v[232:235], v[70:73]
	v_mfma_f32_16x16x32_bf16 v[66:69], v[170:173], v[232:235], v[66:69]
	v_mfma_f32_16x16x32_bf16 v[66:69], v[178:181], v[236:239], v[66:69]
	v_mfma_f32_16x16x32_bf16 v[74:77], v[178:181], v[228:231], v[74:77]
	v_mfma_f32_16x16x32_bf16 v[74:77], v[170:173], v[206:209], v[74:77]
	v_mfma_f32_16x16x32_bf16 v[90:93], v[170:173], v[198:201], v[90:93]
	v_mfma_f32_16x16x32_bf16 v[90:93], v[178:181], v[202:205], v[90:93]
	v_mfma_f32_16x16x32_bf16 v[106:109], v[178:181], v[194:197], v[106:109]
	v_mfma_f32_16x16x32_bf16 v[106:109], v[170:173], v[190:193], v[106:109]
	s_setprio 0
	s_barrier
	s_add_i32 s24, s53, s38
	v_lshl_add_u64 v[140:141], v[140:141], 0, s[34:35]
	s_mov_b32 m0, s24
	ds_read_b128 v[190:193], v145 offset:49152
	ds_read_b128 v[194:197], v145 offset:50176
	ds_read_b128 v[198:201], v145 offset:51200
	ds_read_b128 v[202:205], v145 offset:52224
	ds_read_b128 v[206:209], v145 offset:53248
	ds_read_b128 v[228:231], v145 offset:54272
	ds_read_b128 v[232:235], v145 offset:55296
	ds_read_b128 v[236:239], v145 offset:56320
	global_load_lds_dwordx4 v[140:141], off
	s_add_i32 m0, s24, 0x2000
	s_add_u32 s22, s22, 0x100080
	v_lshl_add_u64 v[140:141], v[186:187], 0, s[34:35]
	s_addc_u32 s23, s23, 0
	s_add_i32 s24, s54, s38
	global_load_lds_dwordx4 v[140:141], off
	v_lshl_add_u64 v[140:141], s[22:23], 0, v[0:1]
	s_mov_b32 m0, s24
	s_nop 0
	global_load_lds_dwordx4 v[140:141], off
	v_lshl_add_u64 v[140:141], s[22:23], 0, v[130:131]
	s_add_i32 m0, s24, 0x2000
	s_nop 0
	global_load_lds_dwordx4 v[140:141], off
	v_lshl_add_u64 v[140:141], v[188:189], 0, s[34:35]
	s_mov_b32 m0, s43
	s_nop 0
	global_load_lds_dwordx4 v[140:141], off
	v_lshl_add_u64 v[140:141], v[210:211], 0, s[34:35]
	s_mov_b32 m0, s44
	s_nop 0
	global_load_lds_dwordx4 v[140:141], off
	s_waitcnt vmcnt(8)
	s_waitcnt lgkmcnt(0)
	s_barrier
	s_setprio 1
	s_waitcnt lgkmcnt(0)
	v_mfma_f32_16x16x32_bf16 v[62:65], v[146:149], v[190:193], v[62:65]
	v_mfma_f32_16x16x32_bf16 v[62:65], v[150:153], v[194:197], v[62:65]
	v_mfma_f32_16x16x32_bf16 v[54:57], v[150:153], v[202:205], v[54:57]
	v_mfma_f32_16x16x32_bf16 v[54:57], v[146:149], v[198:201], v[54:57]
	v_mfma_f32_16x16x32_bf16 v[38:41], v[146:149], v[206:209], v[38:41]
	v_mfma_f32_16x16x32_bf16 v[38:41], v[150:153], v[228:231], v[38:41]
	v_mfma_f32_16x16x32_bf16 v[22:25], v[150:153], v[236:239], v[22:25]
	v_mfma_f32_16x16x32_bf16 v[22:25], v[146:149], v[232:235], v[22:25]
	v_mfma_f32_16x16x32_bf16 v[14:17], v[154:157], v[232:235], v[14:17]
	v_mfma_f32_16x16x32_bf16 v[14:17], v[158:161], v[236:239], v[14:17]
	v_mfma_f32_16x16x32_bf16 v[30:33], v[158:161], v[228:231], v[30:33]
	v_mfma_f32_16x16x32_bf16 v[30:33], v[154:157], v[206:209], v[30:33]
	v_mfma_f32_16x16x32_bf16 v[46:49], v[154:157], v[198:201], v[46:49]
	v_mfma_f32_16x16x32_bf16 v[46:49], v[158:161], v[202:205], v[46:49]
	v_mfma_f32_16x16x32_bf16 v[58:61], v[158:161], v[194:197], v[58:61]
	v_mfma_f32_16x16x32_bf16 v[58:61], v[154:157], v[190:193], v[58:61]
	s_setprio 0
	s_setprio 1
	v_mfma_f32_16x16x32_bf16 v[50:53], v[162:165], v[190:193], v[50:53]
	v_mfma_f32_16x16x32_bf16 v[50:53], v[166:169], v[194:197], v[50:53]
	v_mfma_f32_16x16x32_bf16 v[34:37], v[166:169], v[202:205], v[34:37]
	v_mfma_f32_16x16x32_bf16 v[34:37], v[162:165], v[198:201], v[34:37]
	v_mfma_f32_16x16x32_bf16 v[18:21], v[162:165], v[206:209], v[18:21]
	v_mfma_f32_16x16x32_bf16 v[18:21], v[166:169], v[228:231], v[18:21]
	v_mfma_f32_16x16x32_bf16 v[6:9], v[166:169], v[236:239], v[6:9]
	v_mfma_f32_16x16x32_bf16 v[6:9], v[162:165], v[232:235], v[6:9]
	v_mfma_f32_16x16x32_bf16 v[2:5], v[170:173], v[232:235], v[2:5]
	v_mfma_f32_16x16x32_bf16 v[2:5], v[178:181], v[236:239], v[2:5]
	v_mfma_f32_16x16x32_bf16 v[10:13], v[178:181], v[228:231], v[10:13]
	v_mfma_f32_16x16x32_bf16 v[10:13], v[170:173], v[206:209], v[10:13]
	v_mfma_f32_16x16x32_bf16 v[26:29], v[170:173], v[198:201], v[26:29]
	v_mfma_f32_16x16x32_bf16 v[26:29], v[178:181], v[202:205], v[26:29]
	v_mfma_f32_16x16x32_bf16 v[42:45], v[178:181], v[194:197], v[42:45]
	v_mfma_f32_16x16x32_bf16 v[42:45], v[170:173], v[190:193], v[42:45]
	s_setprio 0
	s_barrier
	s_add_i32 s52, s52, 2
	s_add_u32 s18, s18, 0x100
	s_addc_u32 s19, s19, 0
	s_add_u32 s50, s50, 0x100
	s_addc_u32 s51, s51, 0
	s_cmp_gt_u32 s52, 61
	s_cbranch_scc0 .LBB0_575
	s_and_b64 vcc, exec, s[4:5]
	s_cbranch_vccz .LBB0_578
	s_barrier

.LBB0_721:
	s_add_u32 s18, s16, 0xfff00080
	s_addc_u32 s19, s17, -1
	s_add_i32 s53, 0, 0x10000
	s_cmp_eq_u32 s52, 60
	s_cselect_b32 s23, s7, s19
	s_cselect_b32 s22, s48, s18
	v_add_u32_e32 v140, s53, v143
	s_cselect_b32 s19, s5, s51
	s_cselect_b32 s18, s49, s50
	s_add_i32 s56, 0, 0x14000
	ds_read_b128 v[146:149], v140
	ds_read_b128 v[150:153], v140 offset:1024
	ds_read_b128 v[154:157], v140 offset:2048
	ds_read_b128 v[158:161], v140 offset:3072
	v_add_u32_e32 v140, s56, v143
	ds_read_b128 v[162:165], v140
	ds_read_b128 v[166:169], v140 offset:1024
	ds_read_b128 v[170:173], v140 offset:2048
	ds_read_b128 v[178:181], v140 offset:3072
	v_lshl_add_u64 v[140:141], s[16:17], 0, v[136:137]
	s_add_i32 m0, s31, 0xc000
	ds_read_b128 v[190:193], v145
	ds_read_b128 v[194:197], v145 offset:1024
	ds_read_b128 v[198:201], v145 offset:2048
	ds_read_b128 v[202:205], v145 offset:3072
	ds_read_b128 v[206:209], v145 offset:4096
	ds_read_b128 v[228:231], v145 offset:5120
	ds_read_b128 v[232:235], v145 offset:6144
	ds_read_b128 v[236:239], v145 offset:7168
	global_load_lds_dwordx4 v[140:141], off
	v_lshl_add_u64 v[140:141], s[16:17], 0, v[138:139]
	s_add_i32 m0, s31, 0xe000
	s_nop 0
	global_load_lds_dwordx4 v[140:141], off
	s_waitcnt vmcnt(8)
	s_waitcnt lgkmcnt(0)
	s_barrier
	s_setprio 1
	s_waitcnt lgkmcnt(0)
	v_mfma_f32_16x16x32_bf16 v[126:129], v[146:149], v[190:193], v[126:129]
	v_mfma_f32_16x16x32_bf16 v[126:129], v[150:153], v[194:197], v[126:129]
	v_mfma_f32_16x16x32_bf16 v[110:113], v[150:153], v[202:205], v[110:113]
	v_mfma_f32_16x16x32_bf16 v[110:113], v[146:149], v[198:201], v[110:113]
	v_mfma_f32_16x16x32_bf16 v[94:97], v[146:149], v[206:209], v[94:97]
	v_mfma_f32_16x16x32_bf16 v[94:97], v[150:153], v[228:231], v[94:97]
	v_mfma_f32_16x16x32_bf16 v[78:81], v[150:153], v[236:239], v[78:81]
	v_mfma_f32_16x16x32_bf16 v[78:81], v[146:149], v[232:235], v[78:81]
	v_mfma_f32_16x16x32_bf16 v[70:73], v[154:157], v[232:235], v[70:73]
	v_mfma_f32_16x16x32_bf16 v[70:73], v[158:161], v[236:239], v[70:73]
	v_mfma_f32_16x16x32_bf16 v[86:89], v[158:161], v[228:231], v[86:89]
	v_mfma_f32_16x16x32_bf16 v[86:89], v[154:157], v[206:209], v[86:89]
	v_mfma_f32_16x16x32_bf16 v[102:105], v[154:157], v[198:201], v[102:105]
	v_mfma_f32_16x16x32_bf16 v[102:105], v[158:161], v[202:205], v[102:105]
	v_mfma_f32_16x16x32_bf16 v[118:121], v[158:161], v[194:197], v[118:121]
	v_mfma_f32_16x16x32_bf16 v[118:121], v[154:157], v[190:193], v[118:121]
	s_setprio 0
	s_setprio 1
	v_mfma_f32_16x16x32_bf16 v[122:125], v[162:165], v[190:193], v[122:125]
	v_mfma_f32_16x16x32_bf16 v[122:125], v[166:169], v[194:197], v[122:125]
	v_mfma_f32_16x16x32_bf16 v[106:109], v[166:169], v[202:205], v[106:109]
	v_mfma_f32_16x16x32_bf16 v[106:109], v[162:165], v[198:201], v[106:109]
	v_mfma_f32_16x16x32_bf16 v[90:93], v[162:165], v[206:209], v[90:93]
	v_mfma_f32_16x16x32_bf16 v[90:93], v[166:169], v[228:231], v[90:93]
	v_mfma_f32_16x16x32_bf16 v[74:77], v[166:169], v[236:239], v[74:77]
	v_mfma_f32_16x16x32_bf16 v[74:77], v[162:165], v[232:235], v[74:77]
	v_mfma_f32_16x16x32_bf16 v[66:69], v[170:173], v[232:235], v[66:69]
	v_mfma_f32_16x16x32_bf16 v[66:69], v[178:181], v[236:239], v[66:69]
	v_mfma_f32_16x16x32_bf16 v[82:85], v[178:181], v[228:231], v[82:85]
	v_mfma_f32_16x16x32_bf16 v[82:85], v[170:173], v[206:209], v[82:85]
	v_mfma_f32_16x16x32_bf16 v[98:101], v[170:173], v[198:201], v[98:101]
	v_mfma_f32_16x16x32_bf16 v[98:101], v[178:181], v[202:205], v[98:101]
	v_mfma_f32_16x16x32_bf16 v[114:117], v[178:181], v[194:197], v[114:117]
	v_mfma_f32_16x16x32_bf16 v[114:117], v[170:173], v[190:193], v[114:117]
	s_setprio 0
	s_barrier
	s_add_i32 s53, s53, s26
	v_lshl_add_u64 v[140:141], s[18:19], 0, v[0:1]
	s_mov_b32 m0, s53
	ds_read_b128 v[190:193], v145 offset:16384
	ds_read_b128 v[194:197], v145 offset:17408
	ds_read_b128 v[198:201], v145 offset:18432
	ds_read_b128 v[202:205], v145 offset:19456
	ds_read_b128 v[206:209], v145 offset:20480
	ds_read_b128 v[228:231], v145 offset:21504
	ds_read_b128 v[232:235], v145 offset:22528
	ds_read_b128 v[236:239], v145 offset:23552
	global_load_lds_dwordx4 v[140:141], off
	s_add_i32 m0, s53, 0x2000
	s_add_u32 s54, s18, 0x100000
	v_lshl_add_u64 v[186:187], s[18:19], 0, v[130:131]
	s_addc_u32 s55, s19, 0
	s_add_i32 s53, s56, s26
	global_load_lds_dwordx4 v[186:187], off
	v_lshl_add_u64 v[188:189], s[54:55], 0, v[0:1]
	s_mov_b32 m0, s53
	v_lshl_add_u64 v[210:211], s[22:23], 0, v[132:133]
	global_load_lds_dwordx4 v[188:189], off
	v_lshl_add_u64 v[188:189], s[54:55], 0, v[130:131]
	s_add_i32 m0, s53, 0x2000
	s_nop 0
	global_load_lds_dwordx4 v[188:189], off
	v_lshl_add_u64 v[188:189], s[22:23], 0, v[134:135]
	s_mov_b32 m0, s31
	s_nop 0
	global_load_lds_dwordx4 v[188:189], off
	s_mov_b32 m0, s40
	s_nop 0
	global_load_lds_dwordx4 v[210:211], off
	s_waitcnt vmcnt(8)
	s_waitcnt lgkmcnt(0)
	s_barrier
	s_setprio 1
	s_waitcnt lgkmcnt(0)
	v_mfma_f32_16x16x32_bf16 v[62:65], v[146:149], v[190:193], v[62:65]
	v_mfma_f32_16x16x32_bf16 v[62:65], v[150:153], v[194:197], v[62:65]
	v_mfma_f32_16x16x32_bf16 v[46:49], v[150:153], v[202:205], v[46:49]
	v_mfma_f32_16x16x32_bf16 v[46:49], v[146:149], v[198:201], v[46:49]
	v_mfma_f32_16x16x32_bf16 v[30:33], v[146:149], v[206:209], v[30:33]
	v_mfma_f32_16x16x32_bf16 v[30:33], v[150:153], v[228:231], v[30:33]
	v_mfma_f32_16x16x32_bf16 v[14:17], v[150:153], v[236:239], v[14:17]
	v_mfma_f32_16x16x32_bf16 v[14:17], v[146:149], v[232:235], v[14:17]
	v_mfma_f32_16x16x32_bf16 v[6:9], v[154:157], v[232:235], v[6:9]
	v_mfma_f32_16x16x32_bf16 v[6:9], v[158:161], v[236:239], v[6:9]
	v_mfma_f32_16x16x32_bf16 v[22:25], v[158:161], v[228:231], v[22:25]
	v_mfma_f32_16x16x32_bf16 v[22:25], v[154:157], v[206:209], v[22:25]
	v_mfma_f32_16x16x32_bf16 v[38:41], v[154:157], v[198:201], v[38:41]
	v_mfma_f32_16x16x32_bf16 v[38:41], v[158:161], v[202:205], v[38:41]
	v_mfma_f32_16x16x32_bf16 v[54:57], v[158:161], v[194:197], v[54:57]
	v_mfma_f32_16x16x32_bf16 v[54:57], v[154:157], v[190:193], v[54:57]
	s_setprio 0
	s_setprio 1
	v_mfma_f32_16x16x32_bf16 v[58:61], v[162:165], v[190:193], v[58:61]
	v_mfma_f32_16x16x32_bf16 v[58:61], v[166:169], v[194:197], v[58:61]
	v_mfma_f32_16x16x32_bf16 v[42:45], v[166:169], v[202:205], v[42:45]
	v_mfma_f32_16x16x32_bf16 v[42:45], v[162:165], v[198:201], v[42:45]
	v_mfma_f32_16x16x32_bf16 v[26:29], v[162:165], v[206:209], v[26:29]
	v_mfma_f32_16x16x32_bf16 v[26:29], v[166:169], v[228:231], v[26:29]
	v_mfma_f32_16x16x32_bf16 v[10:13], v[166:169], v[236:239], v[10:13]
	v_mfma_f32_16x16x32_bf16 v[10:13], v[162:165], v[232:235], v[10:13]
	v_mfma_f32_16x16x32_bf16 v[2:5], v[170:173], v[232:235], v[2:5]
	v_mfma_f32_16x16x32_bf16 v[2:5], v[178:181], v[236:239], v[2:5]
	v_mfma_f32_16x16x32_bf16 v[18:21], v[178:181], v[228:231], v[18:21]
	v_mfma_f32_16x16x32_bf16 v[18:21], v[170:173], v[206:209], v[18:21]
	v_mfma_f32_16x16x32_bf16 v[34:37], v[170:173], v[198:201], v[34:37]
	v_mfma_f32_16x16x32_bf16 v[34:37], v[178:181], v[202:205], v[34:37]
	v_mfma_f32_16x16x32_bf16 v[50:53], v[178:181], v[194:197], v[50:53]
	v_mfma_f32_16x16x32_bf16 v[50:53], v[170:173], v[190:193], v[50:53]
	s_setprio 0
	s_barrier
	s_add_i32 s53, 0, 0x18000
	s_add_i32 s54, 0, 0x1c000
	v_add_u32_e32 v158, s53, v143
	v_add_u32_e32 v175, s54, v143
	ds_read_b128 v[146:149], v158
	ds_read_b128 v[150:153], v158 offset:1024
	ds_read_b128 v[154:157], v158 offset:2048
	ds_read_b128 v[158:161], v158 offset:3072
	ds_read_b128 v[162:165], v175
	ds_read_b128 v[166:169], v175 offset:1024
	ds_read_b128 v[170:173], v175 offset:2048
	ds_read_b128 v[178:181], v175 offset:3072
	s_add_u32 s22, s22, 0x100000
	s_addc_u32 s23, s23, 0
	s_mov_b32 m0, s41
	v_lshl_add_u64 v[226:227], s[22:23], 0, v[134:135]
	ds_read_b128 v[190:193], v145 offset:32768
	ds_read_b128 v[194:197], v145 offset:33792
	ds_read_b128 v[198:201], v145 offset:34816
	ds_read_b128 v[202:205], v145 offset:35840
	ds_read_b128 v[206:209], v145 offset:36864
	ds_read_b128 v[228:231], v145 offset:37888
	ds_read_b128 v[232:235], v145 offset:38912
	ds_read_b128 v[236:239], v145 offset:39936
	global_load_lds_dwordx4 v[226:227], off
	v_lshl_add_u64 v[226:227], s[22:23], 0, v[132:133]
	s_mov_b32 m0, s42
	s_nop 0
	global_load_lds_dwordx4 v[226:227], off
	s_waitcnt vmcnt(8)
	s_waitcnt lgkmcnt(0)
	s_barrier
	s_setprio 1
	s_waitcnt lgkmcnt(0)
	v_mfma_f32_16x16x32_bf16 v[126:129], v[146:149], v[190:193], v[126:129]
	v_mfma_f32_16x16x32_bf16 v[126:129], v[150:153], v[194:197], v[126:129]
	v_mfma_f32_16x16x32_bf16 v[110:113], v[150:153], v[202:205], v[110:113]
	v_mfma_f32_16x16x32_bf16 v[110:113], v[146:149], v[198:201], v[110:113]
	v_mfma_f32_16x16x32_bf16 v[94:97], v[146:149], v[206:209], v[94:97]
	v_mfma_f32_16x16x32_bf16 v[94:97], v[150:153], v[228:231], v[94:97]
	v_mfma_f32_16x16x32_bf16 v[78:81], v[150:153], v[236:239], v[78:81]
	v_mfma_f32_16x16x32_bf16 v[78:81], v[146:149], v[232:235], v[78:81]
	v_mfma_f32_16x16x32_bf16 v[70:73], v[154:157], v[232:235], v[70:73]
	v_mfma_f32_16x16x32_bf16 v[70:73], v[158:161], v[236:239], v[70:73]
	v_mfma_f32_16x16x32_bf16 v[86:89], v[158:161], v[228:231], v[86:89]
	v_mfma_f32_16x16x32_bf16 v[86:89], v[154:157], v[206:209], v[86:89]
	v_mfma_f32_16x16x32_bf16 v[102:105], v[154:157], v[198:201], v[102:105]
	v_mfma_f32_16x16x32_bf16 v[102:105], v[158:161], v[202:205], v[102:105]
	v_mfma_f32_16x16x32_bf16 v[118:121], v[158:161], v[194:197], v[118:121]
	v_mfma_f32_16x16x32_bf16 v[118:121], v[154:157], v[190:193], v[118:121]
	s_setprio 0
	s_setprio 1
	v_mfma_f32_16x16x32_bf16 v[122:125], v[162:165], v[190:193], v[122:125]
	v_mfma_f32_16x16x32_bf16 v[122:125], v[166:169], v[194:197], v[122:125]
	v_mfma_f32_16x16x32_bf16 v[106:109], v[166:169], v[202:205], v[106:109]
	v_mfma_f32_16x16x32_bf16 v[106:109], v[162:165], v[198:201], v[106:109]
	v_mfma_f32_16x16x32_bf16 v[90:93], v[162:165], v[206:209], v[90:93]
	v_mfma_f32_16x16x32_bf16 v[90:93], v[166:169], v[228:231], v[90:93]
	v_mfma_f32_16x16x32_bf16 v[74:77], v[166:169], v[236:239], v[74:77]
	v_mfma_f32_16x16x32_bf16 v[74:77], v[162:165], v[232:235], v[74:77]
	v_mfma_f32_16x16x32_bf16 v[66:69], v[170:173], v[232:235], v[66:69]
	v_mfma_f32_16x16x32_bf16 v[66:69], v[178:181], v[236:239], v[66:69]
	v_mfma_f32_16x16x32_bf16 v[82:85], v[178:181], v[228:231], v[82:85]
	v_mfma_f32_16x16x32_bf16 v[82:85], v[170:173], v[206:209], v[82:85]
	v_mfma_f32_16x16x32_bf16 v[98:101], v[170:173], v[198:201], v[98:101]
	v_mfma_f32_16x16x32_bf16 v[98:101], v[178:181], v[202:205], v[98:101]
	v_mfma_f32_16x16x32_bf16 v[114:117], v[178:181], v[194:197], v[114:117]
	v_mfma_f32_16x16x32_bf16 v[114:117], v[170:173], v[190:193], v[114:117]
	s_setprio 0
	s_barrier
	s_add_i32 s22, s53, s26
	v_lshl_add_u64 v[140:141], v[140:141], 0, s[34:35]
	s_mov_b32 m0, s22
	ds_read_b128 v[190:193], v145 offset:49152
	ds_read_b128 v[194:197], v145 offset:50176
	ds_read_b128 v[198:201], v145 offset:51200
	ds_read_b128 v[202:205], v145 offset:52224
	ds_read_b128 v[206:209], v145 offset:53248
	ds_read_b128 v[228:231], v145 offset:54272
	ds_read_b128 v[232:235], v145 offset:55296
	ds_read_b128 v[236:239], v145 offset:56320
	global_load_lds_dwordx4 v[140:141], off
	s_add_i32 m0, s22, 0x2000
	s_add_u32 s18, s18, 0x100080
	v_lshl_add_u64 v[140:141], v[186:187], 0, s[34:35]
	s_addc_u32 s19, s19, 0
	s_add_i32 s22, s54, s26
	global_load_lds_dwordx4 v[140:141], off
	v_lshl_add_u64 v[140:141], s[18:19], 0, v[0:1]
	s_mov_b32 m0, s22
	s_nop 0
	global_load_lds_dwordx4 v[140:141], off
	v_lshl_add_u64 v[140:141], s[18:19], 0, v[130:131]
	s_add_i32 m0, s22, 0x2000
	s_nop 0
	global_load_lds_dwordx4 v[140:141], off
	v_lshl_add_u64 v[140:141], v[188:189], 0, s[34:35]
	s_mov_b32 m0, s43
	s_nop 0
	global_load_lds_dwordx4 v[140:141], off
	v_lshl_add_u64 v[140:141], v[210:211], 0, s[34:35]
	s_mov_b32 m0, s44
	s_nop 0
	global_load_lds_dwordx4 v[140:141], off
	s_waitcnt vmcnt(8)
	s_waitcnt lgkmcnt(0)
	s_barrier
	s_setprio 1
	s_waitcnt lgkmcnt(0)
	v_mfma_f32_16x16x32_bf16 v[62:65], v[146:149], v[190:193], v[62:65]
	v_mfma_f32_16x16x32_bf16 v[62:65], v[150:153], v[194:197], v[62:65]
	v_mfma_f32_16x16x32_bf16 v[46:49], v[150:153], v[202:205], v[46:49]
	v_mfma_f32_16x16x32_bf16 v[46:49], v[146:149], v[198:201], v[46:49]
	v_mfma_f32_16x16x32_bf16 v[30:33], v[146:149], v[206:209], v[30:33]
	v_mfma_f32_16x16x32_bf16 v[30:33], v[150:153], v[228:231], v[30:33]
	v_mfma_f32_16x16x32_bf16 v[14:17], v[150:153], v[236:239], v[14:17]
	v_mfma_f32_16x16x32_bf16 v[14:17], v[146:149], v[232:235], v[14:17]
	v_mfma_f32_16x16x32_bf16 v[6:9], v[154:157], v[232:235], v[6:9]
	v_mfma_f32_16x16x32_bf16 v[6:9], v[158:161], v[236:239], v[6:9]
	v_mfma_f32_16x16x32_bf16 v[22:25], v[158:161], v[228:231], v[22:25]
	v_mfma_f32_16x16x32_bf16 v[22:25], v[154:157], v[206:209], v[22:25]
	v_mfma_f32_16x16x32_bf16 v[38:41], v[154:157], v[198:201], v[38:41]
	v_mfma_f32_16x16x32_bf16 v[38:41], v[158:161], v[202:205], v[38:41]
	v_mfma_f32_16x16x32_bf16 v[54:57], v[158:161], v[194:197], v[54:57]
	v_mfma_f32_16x16x32_bf16 v[54:57], v[154:157], v[190:193], v[54:57]
	s_setprio 0
	s_setprio 1
	v_mfma_f32_16x16x32_bf16 v[58:61], v[162:165], v[190:193], v[58:61]
	v_mfma_f32_16x16x32_bf16 v[58:61], v[166:169], v[194:197], v[58:61]
	v_mfma_f32_16x16x32_bf16 v[42:45], v[166:169], v[202:205], v[42:45]
	v_mfma_f32_16x16x32_bf16 v[42:45], v[162:165], v[198:201], v[42:45]
	v_mfma_f32_16x16x32_bf16 v[26:29], v[162:165], v[206:209], v[26:29]
	v_mfma_f32_16x16x32_bf16 v[26:29], v[166:169], v[228:231], v[26:29]
	v_mfma_f32_16x16x32_bf16 v[10:13], v[166:169], v[236:239], v[10:13]
	v_mfma_f32_16x16x32_bf16 v[10:13], v[162:165], v[232:235], v[10:13]
	v_mfma_f32_16x16x32_bf16 v[2:5], v[170:173], v[232:235], v[2:5]
	v_mfma_f32_16x16x32_bf16 v[2:5], v[178:181], v[236:239], v[2:5]
	v_mfma_f32_16x16x32_bf16 v[18:21], v[178:181], v[228:231], v[18:21]
	v_mfma_f32_16x16x32_bf16 v[18:21], v[170:173], v[206:209], v[18:21]
	v_mfma_f32_16x16x32_bf16 v[34:37], v[170:173], v[198:201], v[34:37]
	v_mfma_f32_16x16x32_bf16 v[34:37], v[178:181], v[202:205], v[34:37]
	v_mfma_f32_16x16x32_bf16 v[50:53], v[178:181], v[194:197], v[50:53]
	v_mfma_f32_16x16x32_bf16 v[50:53], v[170:173], v[190:193], v[50:53]
	s_setprio 0
	s_barrier
	s_add_i32 s52, s52, 2
	s_add_u32 s16, s16, 0x100
	s_addc_u32 s17, s17, 0
	s_add_u32 s50, s50, 0x100
	s_addc_u32 s51, s51, 0
	s_cmp_gt_u32 s52, 61
	s_cbranch_scc0 .LBB0_721
	s_and_b64 vcc, exec, s[2:3]
	s_cbranch_vccz .LBB0_724
	s_barrier

.LBB0_805:
	s_add_u32 s16, s14, 0x100
	s_addc_u32 s17, s15, 0
	s_add_i32 s49, 0, 0x10000
	s_cmpk_eq_i32 s48, 0xa8
	s_cselect_b32 s23, s5, s17
	s_cselect_b32 s22, s4, s16
	v_add_u32_e32 v140, s49, v143
	s_cselect_b32 s19, s9, s47
	s_cselect_b32 s18, s8, s46
	s_add_i32 s50, 0, 0x14000
	ds_read_b128 v[146:149], v140
	ds_read_b128 v[150:153], v140 offset:1024
	ds_read_b128 v[154:157], v140 offset:2048
	ds_read_b128 v[158:161], v140 offset:3072
	v_add_u32_e32 v140, s50, v143
	ds_read_b128 v[162:165], v140
	ds_read_b128 v[166:169], v140 offset:1024
	ds_read_b128 v[170:173], v140 offset:2048
	ds_read_b128 v[178:181], v140 offset:3072
	v_lshl_add_u64 v[140:141], s[14:15], 0, v[136:137]
	s_add_i32 m0, s31, 0xc000
	ds_read_b128 v[190:193], v145
	ds_read_b128 v[194:197], v145 offset:1024
	ds_read_b128 v[198:201], v145 offset:2048
	ds_read_b128 v[202:205], v145 offset:3072
	ds_read_b128 v[206:209], v145 offset:4096
	ds_read_b128 v[228:231], v145 offset:5120
	ds_read_b128 v[232:235], v145 offset:6144
	ds_read_b128 v[236:239], v145 offset:7168
	global_load_lds_dwordx4 v[140:141], off
	v_lshl_add_u64 v[140:141], s[14:15], 0, v[138:139]
	s_add_i32 m0, s31, 0xe000
	s_nop 0
	global_load_lds_dwordx4 v[140:141], off
	s_waitcnt vmcnt(8)
	s_waitcnt lgkmcnt(0)
	s_barrier
	s_setprio 1
	s_waitcnt lgkmcnt(0)
	v_mfma_f32_16x16x32_bf16 v[126:129], v[146:149], v[190:193], v[126:129]
	v_mfma_f32_16x16x32_bf16 v[126:129], v[150:153], v[194:197], v[126:129]
	v_mfma_f32_16x16x32_bf16 v[118:121], v[150:153], v[202:205], v[118:121]
	v_mfma_f32_16x16x32_bf16 v[118:121], v[146:149], v[198:201], v[118:121]
	v_mfma_f32_16x16x32_bf16 v[102:105], v[146:149], v[206:209], v[102:105]
	v_mfma_f32_16x16x32_bf16 v[102:105], v[150:153], v[228:231], v[102:105]
	v_mfma_f32_16x16x32_bf16 v[86:89], v[150:153], v[236:239], v[86:89]
	v_mfma_f32_16x16x32_bf16 v[86:89], v[146:149], v[232:235], v[86:89]
	v_mfma_f32_16x16x32_bf16 v[78:81], v[154:157], v[232:235], v[78:81]
	v_mfma_f32_16x16x32_bf16 v[78:81], v[158:161], v[236:239], v[78:81]
	v_mfma_f32_16x16x32_bf16 v[94:97], v[158:161], v[228:231], v[94:97]
	v_mfma_f32_16x16x32_bf16 v[94:97], v[154:157], v[206:209], v[94:97]
	v_mfma_f32_16x16x32_bf16 v[110:113], v[154:157], v[198:201], v[110:113]
	v_mfma_f32_16x16x32_bf16 v[110:113], v[158:161], v[202:205], v[110:113]
	v_mfma_f32_16x16x32_bf16 v[122:125], v[158:161], v[194:197], v[122:125]
	v_mfma_f32_16x16x32_bf16 v[122:125], v[154:157], v[190:193], v[122:125]
	s_setprio 0
	s_setprio 1
	v_mfma_f32_16x16x32_bf16 v[114:117], v[162:165], v[190:193], v[114:117]
	v_mfma_f32_16x16x32_bf16 v[114:117], v[166:169], v[194:197], v[114:117]
	v_mfma_f32_16x16x32_bf16 v[98:101], v[166:169], v[202:205], v[98:101]
	v_mfma_f32_16x16x32_bf16 v[98:101], v[162:165], v[198:201], v[98:101]
	v_mfma_f32_16x16x32_bf16 v[82:85], v[162:165], v[206:209], v[82:85]
	v_mfma_f32_16x16x32_bf16 v[82:85], v[166:169], v[228:231], v[82:85]
	v_mfma_f32_16x16x32_bf16 v[70:73], v[166:169], v[236:239], v[70:73]
	v_mfma_f32_16x16x32_bf16 v[70:73], v[162:165], v[232:235], v[70:73]
	v_mfma_f32_16x16x32_bf16 v[66:69], v[170:173], v[232:235], v[66:69]
	v_mfma_f32_16x16x32_bf16 v[66:69], v[178:181], v[236:239], v[66:69]
	v_mfma_f32_16x16x32_bf16 v[74:77], v[178:181], v[228:231], v[74:77]
	v_mfma_f32_16x16x32_bf16 v[74:77], v[170:173], v[206:209], v[74:77]
	v_mfma_f32_16x16x32_bf16 v[90:93], v[170:173], v[198:201], v[90:93]
	v_mfma_f32_16x16x32_bf16 v[90:93], v[178:181], v[202:205], v[90:93]
	v_mfma_f32_16x16x32_bf16 v[106:109], v[178:181], v[194:197], v[106:109]
	v_mfma_f32_16x16x32_bf16 v[106:109], v[170:173], v[190:193], v[106:109]
	s_setprio 0
	s_barrier
	s_add_i32 s14, s49, s26
	v_lshl_add_u64 v[140:141], s[18:19], 0, v[0:1]
	s_mov_b32 m0, s14
	ds_read_b128 v[190:193], v145 offset:16384
	ds_read_b128 v[194:197], v145 offset:17408
	ds_read_b128 v[198:201], v145 offset:18432
	ds_read_b128 v[202:205], v145 offset:19456
	ds_read_b128 v[206:209], v145 offset:20480
	ds_read_b128 v[228:231], v145 offset:21504
	ds_read_b128 v[232:235], v145 offset:22528
	ds_read_b128 v[236:239], v145 offset:23552
	global_load_lds_dwordx4 v[140:141], off
	s_add_i32 m0, s14, 0x2000
	s_add_u32 s14, s18, 0x2b0000
	v_lshl_add_u64 v[186:187], s[18:19], 0, v[130:131]
	s_addc_u32 s15, s19, 0
	s_add_i32 s49, s50, s26
	global_load_lds_dwordx4 v[186:187], off
	v_lshl_add_u64 v[188:189], s[14:15], 0, v[0:1]
	s_mov_b32 m0, s49
	v_lshl_add_u64 v[210:211], s[22:23], 0, v[132:133]
	global_load_lds_dwordx4 v[188:189], off
	v_lshl_add_u64 v[188:189], s[14:15], 0, v[130:131]
	s_add_i32 m0, s49, 0x2000
	s_nop 0
	global_load_lds_dwordx4 v[188:189], off
	v_lshl_add_u64 v[188:189], s[22:23], 0, v[134:135]
	s_mov_b32 m0, s31
	s_nop 0
	global_load_lds_dwordx4 v[188:189], off
	s_mov_b32 m0, s36
	s_nop 0
	global_load_lds_dwordx4 v[210:211], off
	s_waitcnt vmcnt(8)
	s_waitcnt lgkmcnt(0)
	s_barrier
	s_setprio 1
	s_waitcnt lgkmcnt(0)
	v_mfma_f32_16x16x32_bf16 v[62:65], v[146:149], v[190:193], v[62:65]
	v_mfma_f32_16x16x32_bf16 v[62:65], v[150:153], v[194:197], v[62:65]
	v_mfma_f32_16x16x32_bf16 v[54:57], v[150:153], v[202:205], v[54:57]
	v_mfma_f32_16x16x32_bf16 v[54:57], v[146:149], v[198:201], v[54:57]
	v_mfma_f32_16x16x32_bf16 v[38:41], v[146:149], v[206:209], v[38:41]
	v_mfma_f32_16x16x32_bf16 v[38:41], v[150:153], v[228:231], v[38:41]
	v_mfma_f32_16x16x32_bf16 v[22:25], v[150:153], v[236:239], v[22:25]
	v_mfma_f32_16x16x32_bf16 v[22:25], v[146:149], v[232:235], v[22:25]
	v_mfma_f32_16x16x32_bf16 v[14:17], v[154:157], v[232:235], v[14:17]
	v_mfma_f32_16x16x32_bf16 v[14:17], v[158:161], v[236:239], v[14:17]
	v_mfma_f32_16x16x32_bf16 v[30:33], v[158:161], v[228:231], v[30:33]
	v_mfma_f32_16x16x32_bf16 v[30:33], v[154:157], v[206:209], v[30:33]
	v_mfma_f32_16x16x32_bf16 v[46:49], v[154:157], v[198:201], v[46:49]
	v_mfma_f32_16x16x32_bf16 v[46:49], v[158:161], v[202:205], v[46:49]
	v_mfma_f32_16x16x32_bf16 v[58:61], v[158:161], v[194:197], v[58:61]
	v_mfma_f32_16x16x32_bf16 v[58:61], v[154:157], v[190:193], v[58:61]
	s_setprio 0
	s_setprio 1
	v_mfma_f32_16x16x32_bf16 v[50:53], v[162:165], v[190:193], v[50:53]
	v_mfma_f32_16x16x32_bf16 v[50:53], v[166:169], v[194:197], v[50:53]
	v_mfma_f32_16x16x32_bf16 v[34:37], v[166:169], v[202:205], v[34:37]
	v_mfma_f32_16x16x32_bf16 v[34:37], v[162:165], v[198:201], v[34:37]
	v_mfma_f32_16x16x32_bf16 v[18:21], v[162:165], v[206:209], v[18:21]
	v_mfma_f32_16x16x32_bf16 v[18:21], v[166:169], v[228:231], v[18:21]
	v_mfma_f32_16x16x32_bf16 v[6:9], v[166:169], v[236:239], v[6:9]
	v_mfma_f32_16x16x32_bf16 v[6:9], v[162:165], v[232:235], v[6:9]
	v_mfma_f32_16x16x32_bf16 v[2:5], v[170:173], v[232:235], v[2:5]
	v_mfma_f32_16x16x32_bf16 v[2:5], v[178:181], v[236:239], v[2:5]
	v_mfma_f32_16x16x32_bf16 v[10:13], v[178:181], v[228:231], v[10:13]
	v_mfma_f32_16x16x32_bf16 v[10:13], v[170:173], v[206:209], v[10:13]
	v_mfma_f32_16x16x32_bf16 v[26:29], v[170:173], v[198:201], v[26:29]
	v_mfma_f32_16x16x32_bf16 v[26:29], v[178:181], v[202:205], v[26:29]
	v_mfma_f32_16x16x32_bf16 v[42:45], v[178:181], v[194:197], v[42:45]
	v_mfma_f32_16x16x32_bf16 v[42:45], v[170:173], v[190:193], v[42:45]
	s_setprio 0
	s_barrier
	s_add_i32 s49, 0, 0x18000
	s_add_i32 s50, 0, 0x1c000
	v_add_u32_e32 v158, s49, v143
	v_add_u32_e32 v175, s50, v143
	ds_read_b128 v[146:149], v158
	ds_read_b128 v[150:153], v158 offset:1024
	ds_read_b128 v[154:157], v158 offset:2048
	ds_read_b128 v[158:161], v158 offset:3072
	ds_read_b128 v[162:165], v175
	ds_read_b128 v[166:169], v175 offset:1024
	ds_read_b128 v[170:173], v175 offset:2048
	ds_read_b128 v[178:181], v175 offset:3072
	s_add_u32 s14, s22, 0x2b0000
	s_addc_u32 s15, s23, 0
	s_mov_b32 m0, s37
	v_lshl_add_u64 v[226:227], s[14:15], 0, v[134:135]
	ds_read_b128 v[190:193], v145 offset:32768
	ds_read_b128 v[194:197], v145 offset:33792
	ds_read_b128 v[198:201], v145 offset:34816
	ds_read_b128 v[202:205], v145 offset:35840
	ds_read_b128 v[206:209], v145 offset:36864
	ds_read_b128 v[228:231], v145 offset:37888
	ds_read_b128 v[232:235], v145 offset:38912
	ds_read_b128 v[236:239], v145 offset:39936
	global_load_lds_dwordx4 v[226:227], off
	v_lshl_add_u64 v[226:227], s[14:15], 0, v[132:133]
	s_mov_b32 m0, s38
	s_nop 0
	global_load_lds_dwordx4 v[226:227], off
	s_waitcnt vmcnt(8)
	s_waitcnt lgkmcnt(0)
	s_barrier
	s_setprio 1
	s_waitcnt lgkmcnt(0)
	v_mfma_f32_16x16x32_bf16 v[126:129], v[146:149], v[190:193], v[126:129]
	v_mfma_f32_16x16x32_bf16 v[126:129], v[150:153], v[194:197], v[126:129]
	v_mfma_f32_16x16x32_bf16 v[118:121], v[150:153], v[202:205], v[118:121]
	v_mfma_f32_16x16x32_bf16 v[118:121], v[146:149], v[198:201], v[118:121]
	v_mfma_f32_16x16x32_bf16 v[102:105], v[146:149], v[206:209], v[102:105]
	v_mfma_f32_16x16x32_bf16 v[102:105], v[150:153], v[228:231], v[102:105]
	v_mfma_f32_16x16x32_bf16 v[86:89], v[150:153], v[236:239], v[86:89]
	v_mfma_f32_16x16x32_bf16 v[86:89], v[146:149], v[232:235], v[86:89]
	v_mfma_f32_16x16x32_bf16 v[78:81], v[154:157], v[232:235], v[78:81]
	v_mfma_f32_16x16x32_bf16 v[78:81], v[158:161], v[236:239], v[78:81]
	v_mfma_f32_16x16x32_bf16 v[94:97], v[158:161], v[228:231], v[94:97]
	v_mfma_f32_16x16x32_bf16 v[94:97], v[154:157], v[206:209], v[94:97]
	v_mfma_f32_16x16x32_bf16 v[110:113], v[154:157], v[198:201], v[110:113]
	v_mfma_f32_16x16x32_bf16 v[110:113], v[158:161], v[202:205], v[110:113]
	v_mfma_f32_16x16x32_bf16 v[122:125], v[158:161], v[194:197], v[122:125]
	v_mfma_f32_16x16x32_bf16 v[122:125], v[154:157], v[190:193], v[122:125]
	s_setprio 0
	s_setprio 1
	v_mfma_f32_16x16x32_bf16 v[114:117], v[162:165], v[190:193], v[114:117]
	v_mfma_f32_16x16x32_bf16 v[114:117], v[166:169], v[194:197], v[114:117]
	v_mfma_f32_16x16x32_bf16 v[98:101], v[166:169], v[202:205], v[98:101]
	v_mfma_f32_16x16x32_bf16 v[98:101], v[162:165], v[198:201], v[98:101]
	v_mfma_f32_16x16x32_bf16 v[82:85], v[162:165], v[206:209], v[82:85]
	v_mfma_f32_16x16x32_bf16 v[82:85], v[166:169], v[228:231], v[82:85]
	v_mfma_f32_16x16x32_bf16 v[70:73], v[166:169], v[236:239], v[70:73]
	v_mfma_f32_16x16x32_bf16 v[70:73], v[162:165], v[232:235], v[70:73]
	v_mfma_f32_16x16x32_bf16 v[66:69], v[170:173], v[232:235], v[66:69]
	v_mfma_f32_16x16x32_bf16 v[66:69], v[178:181], v[236:239], v[66:69]
	v_mfma_f32_16x16x32_bf16 v[74:77], v[178:181], v[228:231], v[74:77]
	v_mfma_f32_16x16x32_bf16 v[74:77], v[170:173], v[206:209], v[74:77]
	v_mfma_f32_16x16x32_bf16 v[90:93], v[170:173], v[198:201], v[90:93]
	v_mfma_f32_16x16x32_bf16 v[90:93], v[178:181], v[202:205], v[90:93]
	v_mfma_f32_16x16x32_bf16 v[106:109], v[178:181], v[194:197], v[106:109]
	v_mfma_f32_16x16x32_bf16 v[106:109], v[170:173], v[190:193], v[106:109]
	s_setprio 0
	s_barrier
	s_add_i32 s14, s49, s26
	v_lshl_add_u64 v[140:141], v[140:141], 0, s[34:35]
	s_mov_b32 m0, s14
	ds_read_b128 v[190:193], v145 offset:49152
	ds_read_b128 v[194:197], v145 offset:50176
	ds_read_b128 v[198:201], v145 offset:51200
	ds_read_b128 v[202:205], v145 offset:52224
	ds_read_b128 v[206:209], v145 offset:53248
	ds_read_b128 v[228:231], v145 offset:54272
	ds_read_b128 v[232:235], v145 offset:55296
	ds_read_b128 v[236:239], v145 offset:56320
	global_load_lds_dwordx4 v[140:141], off
	s_add_i32 m0, s14, 0x2000
	s_add_u32 s14, s18, 0x2b0080
	v_lshl_add_u64 v[140:141], v[186:187], 0, s[34:35]
	s_addc_u32 s15, s19, 0
	s_add_i32 s18, s50, s26
	global_load_lds_dwordx4 v[140:141], off
	v_lshl_add_u64 v[140:141], s[14:15], 0, v[0:1]
	s_mov_b32 m0, s18
	s_nop 0
	global_load_lds_dwordx4 v[140:141], off
	v_lshl_add_u64 v[140:141], s[14:15], 0, v[130:131]
	s_add_i32 m0, s18, 0x2000
	s_nop 0
	global_load_lds_dwordx4 v[140:141], off
	v_lshl_add_u64 v[140:141], v[188:189], 0, s[34:35]
	s_mov_b32 m0, s39
	s_nop 0
	global_load_lds_dwordx4 v[140:141], off
	v_lshl_add_u64 v[140:141], v[210:211], 0, s[34:35]
	s_mov_b32 m0, s40
	s_nop 0
	global_load_lds_dwordx4 v[140:141], off
	s_waitcnt vmcnt(8)
	s_waitcnt lgkmcnt(0)
	s_barrier
	s_setprio 1
	s_waitcnt lgkmcnt(0)
	v_mfma_f32_16x16x32_bf16 v[62:65], v[146:149], v[190:193], v[62:65]
	v_mfma_f32_16x16x32_bf16 v[62:65], v[150:153], v[194:197], v[62:65]
	v_mfma_f32_16x16x32_bf16 v[54:57], v[150:153], v[202:205], v[54:57]
	v_mfma_f32_16x16x32_bf16 v[54:57], v[146:149], v[198:201], v[54:57]
	v_mfma_f32_16x16x32_bf16 v[38:41], v[146:149], v[206:209], v[38:41]
	v_mfma_f32_16x16x32_bf16 v[38:41], v[150:153], v[228:231], v[38:41]
	v_mfma_f32_16x16x32_bf16 v[22:25], v[150:153], v[236:239], v[22:25]
	v_mfma_f32_16x16x32_bf16 v[22:25], v[146:149], v[232:235], v[22:25]
	v_mfma_f32_16x16x32_bf16 v[14:17], v[154:157], v[232:235], v[14:17]
	v_mfma_f32_16x16x32_bf16 v[14:17], v[158:161], v[236:239], v[14:17]
	v_mfma_f32_16x16x32_bf16 v[30:33], v[158:161], v[228:231], v[30:33]
	v_mfma_f32_16x16x32_bf16 v[30:33], v[154:157], v[206:209], v[30:33]
	v_mfma_f32_16x16x32_bf16 v[46:49], v[154:157], v[198:201], v[46:49]
	v_mfma_f32_16x16x32_bf16 v[46:49], v[158:161], v[202:205], v[46:49]
	v_mfma_f32_16x16x32_bf16 v[58:61], v[158:161], v[194:197], v[58:61]
	v_mfma_f32_16x16x32_bf16 v[58:61], v[154:157], v[190:193], v[58:61]
	s_setprio 0
	s_setprio 1
	v_mfma_f32_16x16x32_bf16 v[50:53], v[162:165], v[190:193], v[50:53]
	v_mfma_f32_16x16x32_bf16 v[50:53], v[166:169], v[194:197], v[50:53]
	v_mfma_f32_16x16x32_bf16 v[34:37], v[166:169], v[202:205], v[34:37]
	v_mfma_f32_16x16x32_bf16 v[34:37], v[162:165], v[198:201], v[34:37]
	v_mfma_f32_16x16x32_bf16 v[18:21], v[162:165], v[206:209], v[18:21]
	v_mfma_f32_16x16x32_bf16 v[18:21], v[166:169], v[228:231], v[18:21]
	v_mfma_f32_16x16x32_bf16 v[6:9], v[166:169], v[236:239], v[6:9]
	v_mfma_f32_16x16x32_bf16 v[6:9], v[162:165], v[232:235], v[6:9]
	v_mfma_f32_16x16x32_bf16 v[2:5], v[170:173], v[232:235], v[2:5]
	v_mfma_f32_16x16x32_bf16 v[2:5], v[178:181], v[236:239], v[2:5]
	v_mfma_f32_16x16x32_bf16 v[10:13], v[178:181], v[228:231], v[10:13]
	v_mfma_f32_16x16x32_bf16 v[10:13], v[170:173], v[206:209], v[10:13]
	v_mfma_f32_16x16x32_bf16 v[26:29], v[170:173], v[198:201], v[26:29]
	v_mfma_f32_16x16x32_bf16 v[26:29], v[178:181], v[202:205], v[26:29]
	v_mfma_f32_16x16x32_bf16 v[42:45], v[178:181], v[194:197], v[42:45]
	v_mfma_f32_16x16x32_bf16 v[42:45], v[170:173], v[190:193], v[42:45]
	s_setprio 0
	s_barrier
	s_add_i32 s48, s48, 2
	s_add_u32 s46, s46, 0x100
	s_addc_u32 s47, s47, 0
	s_cmpk_gt_u32 s48, 0xa9
	s_mov_b64 s[14:15], s[16:17]
	s_cbranch_scc0 .LBB0_805
	s_and_b64 vcc, exec, s[6:7]
	s_cbranch_vccz .LBB0_808
	s_barrier
